# barrier leader releases the XCD before waiting for its own L1 invalidate (release no longer serialised behind the invalidate)
# baseline (speedup 1.0000x reference)
; __device__ __forceinline__ unsigned xb_ld(unsigned* p)              { return __hip_atomic_load(p, __ATOMIC_RELAXED, __HIP_MEMORY_SCOPE_AGENT); }
; __device__ __forceinline__ unsigned xb_add(unsigned* p, unsigned v) { return __hip_atomic_fetch_add(p, v, __ATOMIC_RELAXED, __HIP_MEMORY_SCOPE_AGENT); }
; #define XB_SPIN(cond, bar) do { unsigned _sp = 0; while (cond) { __builtin_amdgcn_s_sleep(1); \
;     if ((++_sp & 255u) == 0u) { if (xb_ld(&(bar)[XB_TMO])) break; if (_sp > XB_SPIN_CAP) { atomicAdd(&(bar)[XB_TMO], 1u); break; } } } } while (0)
; __device__ __forceinline__ void xcd_barrier(const XcdBarrier& b) {
;     ...
;         if (old + 1u == (gen + 1u) * nloc) {
;             __builtin_amdgcn_fence(__ATOMIC_RELEASE, "agent");
;             asm volatile("s_waitcnt vmcnt(0)" ::: "memory");
;             const unsigned og = xb_add(&bar[XB_TOP], 1u);
;             const unsigned tg = og / nx;
;             if (og + 1u == (tg + 1u) * nx) xb_add(&bar[XB_TOPGEN], 1u);
;             else XB_SPIN(xb_ld(&bar[XB_TOPGEN]) == tg, bar);
;             __builtin_amdgcn_fence(__ATOMIC_ACQUIRE, "agent");
;             xb_add(&bar[XB_XGEN(b.x)], 1u);
;             asm volatile("s_waitcnt vmcnt(0)" ::: "memory");
.Lxb_local_release:
	s_mov_b64 s[6:7], exec
	v_mbcnt_lo_u32_b32 v0, s6, 0
	v_mbcnt_hi_u32_b32 v0, s7, v0
	v_cmp_eq_u32_e32 vcc, 0, v0
	s_and_saveexec_b64 s[8:9], vcc
	s_cbranch_execz .LBB0_62
	s_bcnt1_i32_b64 s0, s[6:7]
	v_mov_b32_e32 v0, s0
	v_readlane_b32 s0, v254, 47
	v_readlane_b32 s1, v254, 48
	s_nop 4
	global_atomic_add v209, v0, s[0:1]
	s_branch .LBB0_62
